# band attention: running-max offset carried in a 16-register block fed as srcC of the first QK MFMAs (scores come out already max-subtracted; the 16 packed subtracts, the alpha exp and the rescale run
# baseline (speedup 1.0000x reference)
.LBB0_450:
	s_or_b64 exec, exec, s[26:27]
	s_ashr_i32 s23, s23, 8
	s_lshl_b32 s62, s23, 2
	s_add_i32 s23, s62, -8
	s_cmpk_gt_i32 s92, 0x2ff
	s_cselect_b32 s23, s23, 0
	s_or_b32 s24, s62, 3
	s_cmp_le_i32 s23, s24
	s_cbranch_scc0 .LBB0_465
	s_lshl_b32 s60, s23, 6
	s_add_i32 s60, s60, s93
	v_add_u32_e32 v4, s60, v150
	v_ashrrev_i32_e32 v5, 31, v4
	v_lshlrev_b64 v[4:5], 11, v[4:5]
	s_lshl_b64 s[26:27], s[16:17], 1
	v_lshl_add_u64 v[6:7], s[50:51], 0, v[4:5]
	v_lshl_add_u64 v[4:5], s[48:49], 0, v[4:5]
	v_lshl_add_u64 v[6:7], v[6:7], 0, s[26:27]
	v_lshl_add_u64 v[4:5], v[4:5], 0, s[26:27]
	v_lshl_add_u64 v[6:7], v[6:7], 0, v[108:109]
	v_lshl_add_u64 v[4:5], v[4:5], 0, v[108:109]
	s_add_i32 s62, s62, s29
	v_mov_b32_e32 v16, v3
	v_mov_b32_e32 v17, v3
	s_sub_i32 s64, s62, s23
	v_mov_b32_e32 v2, v3
	v_mov_b32_e32 v4, v3
	v_mov_b32_e32 v5, v3
	v_mov_b32_e32 v6, v3
	v_mov_b32_e32 v7, v3
	v_mov_b32_e32 v8, v3
	v_mov_b32_e32 v9, v3
	v_mov_b32_e32 v10, v3
	v_mov_b32_e32 v11, v3
	v_mov_b32_e32 v12, v3
	v_mov_b32_e32 v13, v3
	v_mov_b32_e32 v14, v3
	v_mov_b32_e32 v15, v3
	v_mov_b64_e32 v[48:49], v[16:17]
	v_mov_b64_e32 v[32:33], v[16:17]
	v_lshl_add_u64 v[124:125], v[110:111], 0, s[26:27]
	v_lshl_add_u64 v[126:127], v[112:113], 0, s[26:27]
	s_add_i32 s63, s62, -8
	v_lshl_add_u32 v119, s64, 6, v162
	v_add_u32_e32 v128, s60, v163
	v_mov_b32_e32 v173, 0xf149f2ca
	v_mov_b32_e32 v172, 0
	v_mov_b64_e32 v[46:47], v[14:15]
	v_mov_b64_e32 v[44:45], v[12:13]
	v_mov_b64_e32 v[42:43], v[10:11]
	v_mov_b64_e32 v[40:41], v[8:9]
	v_mov_b64_e32 v[38:39], v[6:7]
	v_mov_b64_e32 v[36:37], v[4:5]
	v_mov_b64_e32 v[34:35], v[2:3]
	v_mov_b64_e32 v[30:31], v[14:15]
	v_mov_b64_e32 v[28:29], v[12:13]
	v_mov_b64_e32 v[26:27], v[10:11]
	v_mov_b64_e32 v[24:25], v[8:9]
	v_mov_b64_e32 v[22:23], v[6:7]
	v_mov_b64_e32 v[20:21], v[4:5]
	v_mov_b64_e32 v[18:19], v[2:3]
	s_mov_b32 s99, 0xff7fffff
	v_mov_b32_e32 v226, 0
	v_mov_b32_e32 v227, 0
	v_mov_b32_e32 v228, 0
	v_mov_b32_e32 v229, 0
	v_mov_b32_e32 v230, 0
	v_mov_b32_e32 v231, 0
	v_mov_b32_e32 v232, 0
	v_mov_b32_e32 v233, 0
	v_mov_b32_e32 v234, 0
	v_mov_b32_e32 v235, 0
	v_mov_b32_e32 v236, 0
	v_mov_b32_e32 v237, 0
	v_mov_b32_e32 v238, 0
	v_mov_b32_e32 v239, 0
	v_mov_b32_e32 v240, 0
	v_mov_b32_e32 v241, 0

.LBB0_454:
	s_cmp_le_i32 s23, s62
	s_cselect_b64 s[60:61], -1, 0
	s_cmp_ge_i32 s23, s63
	s_cselect_b64 s[66:67], -1, 0
	s_and_b64 s[60:61], s[60:61], s[66:67]
	s_andn2_b64 vcc, exec, s[60:61]
	s_cbranch_vccnz .LBB0_462
	ds_read_b32 v220, v3 offset:22528
	ds_read_b128 v[4:7], v165
	ds_read_b128 v[8:11], v165 offset:32
	ds_read_b128 v[12:15], v165 offset:4608
	ds_read_b128 v[130:133], v165 offset:64
	ds_read_b128 v[134:137], v165 offset:4640
	ds_read_b128 v[138:141], v165 offset:4672
	s_waitcnt lgkmcnt(5)
	v_mfma_f32_32x32x16_bf16 v[50:65], v[4:7], v[82:85], v[226:241]
	ds_read_b128 v[4:7], v165 offset:96
	ds_read_b128 v[142:145], v165 offset:4704
	s_waitcnt lgkmcnt(5)
	v_mfma_f32_32x32x16_bf16 v[66:81], v[12:15], v[82:85], v[226:241]
	v_mfma_f32_32x32x16_bf16 v[50:65], v[8:11], v[86:89], v[50:65]
	s_waitcnt lgkmcnt(3)
	v_mfma_f32_32x32x16_bf16 v[66:81], v[134:137], v[86:89], v[66:81]
	v_mfma_f32_32x32x16_bf16 v[50:65], v[130:133], v[90:93], v[50:65]
	s_waitcnt lgkmcnt(2)
	v_mfma_f32_32x32x16_bf16 v[66:81], v[138:141], v[90:93], v[66:81]
	s_waitcnt lgkmcnt(1)
	v_mfma_f32_32x32x16_bf16 v[50:65], v[4:7], v[94:97], v[50:65]
	s_waitcnt lgkmcnt(0)
	v_mfma_f32_32x32x16_bf16 v[66:81], v[142:145], v[94:97], v[66:81]
	s_cmp_lt_i32 s64, 3
	s_mov_b64 s[60:61], -1
	s_cbranch_scc0 .LBB0_457
	v_lshlrev_b32_e32 v186, 2, v119
	s_cmp_lt_i32 s64, 2
	s_cbranch_scc0 .Lbg_clamp
	ds_read_b32 v4, v186 offset:21504
	ds_read_b32 v5, v186 offset:21500
	ds_read_b32 v6, v186 offset:21496
	ds_read_b32 v7, v186 offset:21492
	ds_read_b32 v8, v186 offset:21488
	ds_read_b32 v9, v186 offset:21484
	ds_read_b32 v10, v186 offset:21480
	ds_read_b32 v11, v186 offset:21476
	ds_read_b32 v12, v186 offset:21440
	ds_read_b32 v13, v186 offset:21436
	ds_read_b32 v14, v186 offset:21432
	ds_read_b32 v15, v186 offset:21428
	ds_read_b32 v130, v186 offset:21424
	ds_read_b32 v131, v186 offset:21420
	ds_read_b32 v16, v186 offset:21416
	ds_read_b32 v17, v186 offset:21412
	ds_read_b32 v136, v186 offset:21376
	ds_read_b32 v137, v186 offset:21372
	ds_read_b32 v132, v186 offset:21368
	ds_read_b32 v133, v186 offset:21364
	ds_read_b32 v174, v186 offset:21360
	ds_read_b32 v175, v186 offset:21356
	ds_read_b32 v176, v186 offset:21352
	ds_read_b32 v177, v186 offset:21348
	ds_read_b32 v178, v186 offset:21312
	ds_read_b32 v179, v186 offset:21308
	ds_read_b32 v180, v186 offset:21304
	ds_read_b32 v181, v186 offset:21300
	ds_read_b32 v182, v186 offset:21296
	ds_read_b32 v183, v186 offset:21292
	ds_read_b32 v184, v186 offset:21288
	ds_read_b32 v185, v186 offset:21284
	s_branch .Lbg_tail

.Lbg_tail:
	s_waitcnt lgkmcnt(14)
	v_pk_add_f32 v[64:65], v[64:65], v[16:17]
	v_pk_add_f32 v[62:63], v[62:63], v[130:131]
	v_pk_add_f32 v[60:61], v[60:61], v[14:15]
	v_pk_add_f32 v[58:59], v[58:59], v[12:13]
	v_pk_add_f32 v[56:57], v[56:57], v[10:11]
	v_pk_add_f32 v[54:55], v[54:55], v[8:9]
	v_pk_add_f32 v[52:53], v[52:53], v[6:7]
	v_pk_add_f32 v[50:51], v[50:51], v[4:5]
	s_waitcnt lgkmcnt(0)
	v_pk_add_f32 v[80:81], v[80:81], v[184:185]
	v_pk_add_f32 v[78:79], v[78:79], v[182:183]
	v_pk_add_f32 v[76:77], v[76:77], v[180:181]
	v_pk_add_f32 v[74:75], v[74:75], v[178:179]
	v_pk_add_f32 v[72:73], v[72:73], v[176:177]
	v_pk_add_f32 v[70:71], v[70:71], v[174:175]
	v_pk_add_f32 v[68:69], v[68:69], v[132:133]
	v_pk_add_f32 v[66:67], v[66:67], v[136:137]
	v_pk_add_f32 v[64:65], v[64:65], v[220:221] op_sel_hi:[1,0] neg_lo:[0,1] neg_hi:[0,1]
	v_pk_add_f32 v[62:63], v[62:63], v[220:221] op_sel_hi:[1,0] neg_lo:[0,1] neg_hi:[0,1]
	v_pk_add_f32 v[60:61], v[60:61], v[220:221] op_sel_hi:[1,0] neg_lo:[0,1] neg_hi:[0,1]
	v_pk_add_f32 v[58:59], v[58:59], v[220:221] op_sel_hi:[1,0] neg_lo:[0,1] neg_hi:[0,1]
	v_pk_add_f32 v[56:57], v[56:57], v[220:221] op_sel_hi:[1,0] neg_lo:[0,1] neg_hi:[0,1]
	v_pk_add_f32 v[54:55], v[54:55], v[220:221] op_sel_hi:[1,0] neg_lo:[0,1] neg_hi:[0,1]
	v_pk_add_f32 v[52:53], v[52:53], v[220:221] op_sel_hi:[1,0] neg_lo:[0,1] neg_hi:[0,1]
	v_pk_add_f32 v[50:51], v[50:51], v[220:221] op_sel_hi:[1,0] neg_lo:[0,1] neg_hi:[0,1]
	v_pk_add_f32 v[80:81], v[80:81], v[220:221] op_sel_hi:[1,0] neg_lo:[0,1] neg_hi:[0,1]
	v_pk_add_f32 v[78:79], v[78:79], v[220:221] op_sel_hi:[1,0] neg_lo:[0,1] neg_hi:[0,1]
	v_pk_add_f32 v[76:77], v[76:77], v[220:221] op_sel_hi:[1,0] neg_lo:[0,1] neg_hi:[0,1]
	v_pk_add_f32 v[74:75], v[74:75], v[220:221] op_sel_hi:[1,0] neg_lo:[0,1] neg_hi:[0,1]
	v_pk_add_f32 v[72:73], v[72:73], v[220:221] op_sel_hi:[1,0] neg_lo:[0,1] neg_hi:[0,1]
	v_pk_add_f32 v[70:71], v[70:71], v[220:221] op_sel_hi:[1,0] neg_lo:[0,1] neg_hi:[0,1]
	v_pk_add_f32 v[68:69], v[68:69], v[220:221] op_sel_hi:[1,0] neg_lo:[0,1] neg_hi:[0,1]
	v_pk_add_f32 v[66:67], v[66:67], v[220:221] op_sel_hi:[1,0] neg_lo:[0,1] neg_hi:[0,1]
	s_mov_b64 s[60:61], 0

.LBB0_459:
	ds_read_b64_tr_b16 v[188:189], v153 offset:9216
	ds_read_b64_tr_b16 v[190:191], v153 offset:9984
	ds_read_b64_tr_b16 v[192:193], v153 offset:9280
	ds_read_b64_tr_b16 v[194:195], v153 offset:10048
	ds_read_b64_tr_b16 v[196:197], v153 offset:12288
	ds_read_b64_tr_b16 v[198:199], v153 offset:13056
	ds_read_b64_tr_b16 v[200:201], v153 offset:12352
	ds_read_b64_tr_b16 v[202:203], v153 offset:13120
	ds_read_b64_tr_b16 v[204:205], v153 offset:15360
	ds_read_b64_tr_b16 v[206:207], v153 offset:16128
	ds_read_b64_tr_b16 v[208:209], v153 offset:15424
	ds_read_b64_tr_b16 v[210:211], v153 offset:16192
	ds_read_b64_tr_b16 v[212:213], v153 offset:18432
	ds_read_b64_tr_b16 v[214:215], v153 offset:19200
	ds_read_b64_tr_b16 v[216:217], v153 offset:18496
	ds_read_b64_tr_b16 v[218:219], v153 offset:19264
	s_nop 0
	v_max_f32_e32 v2, v51, v51
	s_nop 2
	v_max_f32_e32 v225, v50, v50
	v_max_f32_e32 v2, v225, v2
	v_max3_f32 v2, v2, v52, v53
	v_max3_f32 v2, v2, v54, v55
	v_max3_f32 v2, v2, v56, v57
	v_max3_f32 v2, v2, v58, v59
	v_max3_f32 v2, v2, v60, v61
	v_max3_f32 v2, v2, v62, v63
	v_max3_f32 v2, v2, v64, v65
	v_max3_f32 v2, v2, v66, v67
	v_max3_f32 v2, v2, v68, v69
	v_max3_f32 v2, v2, v70, v71
	v_max3_f32 v2, v2, v72, v73
	v_max3_f32 v2, v2, v74, v75
	v_max3_f32 v2, v2, v76, v77
	v_max3_f32 v2, v2, v78, v79
	v_max3_f32 v2, v2, v80, v81
	v_mov_b32_e32 v225, v2
	s_nop 1
	v_permlane32_swap_b32_e32 v225, v2
	v_max_f32_e32 v224, v2, v225
	v_cmp_lt_f32_e32 vcc, s99, v224
	s_mov_b32 s99, 0x41000000
	s_cbranch_vccz .Lbf_fast
	s_nop 0
	v_cndmask_b32_e32 v224, 0, v224, vcc
	v_sub_f32_e32 v2, 0, v224
	v_exp_f32_e32 v2, v2
	v_sub_f32_e32 v225, v226, v224
	v_mov_b32_e32 v226, v225
	v_mov_b32_e32 v227, v225
	v_mov_b32_e32 v228, v225
	v_mov_b32_e32 v229, v225
	v_mov_b32_e32 v230, v225
	v_mov_b32_e32 v231, v225
	v_mov_b32_e32 v232, v225
	v_mov_b32_e32 v233, v225
	v_mov_b32_e32 v234, v225
	v_mov_b32_e32 v235, v225
	v_mov_b32_e32 v236, v225
	v_mov_b32_e32 v237, v225
	v_mov_b32_e32 v238, v225
	v_mov_b32_e32 v239, v225
	v_mov_b32_e32 v240, v225
	v_mov_b32_e32 v241, v225
	v_mul_f32_e32 v48, v2, v48
	v_mul_f32_e32 v49, v2, v49
	v_mul_f32_e32 v46, v2, v46
	v_mul_f32_e32 v47, v2, v47
	v_mul_f32_e32 v44, v2, v44
	v_mul_f32_e32 v45, v2, v45
	v_mul_f32_e32 v42, v2, v42
	v_mul_f32_e32 v43, v2, v43
	v_mul_f32_e32 v40, v2, v40
	v_mul_f32_e32 v41, v2, v41
	v_mul_f32_e32 v38, v2, v38
	v_mul_f32_e32 v39, v2, v39
	v_mul_f32_e32 v36, v2, v36
	v_mul_f32_e32 v37, v2, v37
	v_mul_f32_e32 v34, v2, v34
	v_mul_f32_e32 v35, v2, v35
	v_mul_f32_e32 v32, v2, v32
	v_mul_f32_e32 v33, v2, v33
	v_mul_f32_e32 v30, v2, v30
	v_mul_f32_e32 v31, v2, v31
	v_mul_f32_e32 v28, v2, v28
	v_mul_f32_e32 v29, v2, v29
	v_mul_f32_e32 v26, v2, v26
	v_mul_f32_e32 v27, v2, v27
	v_mul_f32_e32 v24, v2, v24
	v_mul_f32_e32 v25, v2, v25
	v_mul_f32_e32 v22, v2, v22
	v_mul_f32_e32 v23, v2, v23
	v_mul_f32_e32 v20, v2, v20
	v_mul_f32_e32 v21, v2, v21
	v_mul_f32_e32 v18, v2, v18
	v_mul_f32_e32 v19, v2, v19
	v_pk_add_f32 v[50:51], v[50:51], v[224:225] op_sel_hi:[1,0] neg_lo:[0,1] neg_hi:[0,1]
	v_pk_add_f32 v[52:53], v[52:53], v[224:225] op_sel_hi:[1,0] neg_lo:[0,1] neg_hi:[0,1]
	v_pk_add_f32 v[54:55], v[54:55], v[224:225] op_sel_hi:[1,0] neg_lo:[0,1] neg_hi:[0,1]
	v_pk_add_f32 v[56:57], v[56:57], v[224:225] op_sel_hi:[1,0] neg_lo:[0,1] neg_hi:[0,1]
	v_pk_add_f32 v[58:59], v[58:59], v[224:225] op_sel_hi:[1,0] neg_lo:[0,1] neg_hi:[0,1]
	v_pk_add_f32 v[60:61], v[60:61], v[224:225] op_sel_hi:[1,0] neg_lo:[0,1] neg_hi:[0,1]
	v_pk_add_f32 v[62:63], v[62:63], v[224:225] op_sel_hi:[1,0] neg_lo:[0,1] neg_hi:[0,1]
	v_pk_add_f32 v[64:65], v[64:65], v[224:225] op_sel_hi:[1,0] neg_lo:[0,1] neg_hi:[0,1]
	v_pk_add_f32 v[66:67], v[66:67], v[224:225] op_sel_hi:[1,0] neg_lo:[0,1] neg_hi:[0,1]
	v_pk_add_f32 v[68:69], v[68:69], v[224:225] op_sel_hi:[1,0] neg_lo:[0,1] neg_hi:[0,1]
	v_pk_add_f32 v[70:71], v[70:71], v[224:225] op_sel_hi:[1,0] neg_lo:[0,1] neg_hi:[0,1]
	v_pk_add_f32 v[72:73], v[72:73], v[224:225] op_sel_hi:[1,0] neg_lo:[0,1] neg_hi:[0,1]
	v_pk_add_f32 v[74:75], v[74:75], v[224:225] op_sel_hi:[1,0] neg_lo:[0,1] neg_hi:[0,1]
	v_pk_add_f32 v[76:77], v[76:77], v[224:225] op_sel_hi:[1,0] neg_lo:[0,1] neg_hi:[0,1]
	v_pk_add_f32 v[78:79], v[78:79], v[224:225] op_sel_hi:[1,0] neg_lo:[0,1] neg_hi:[0,1]
	v_pk_add_f32 v[80:81], v[80:81], v[224:225] op_sel_hi:[1,0] neg_lo:[0,1] neg_hi:[0,1]
	s_branch .LBB0_461
.Lbf_fast:
	v_mov_b32_e32 v2, 1.0
.LBB0_461:
	v_exp_f32_e32 v4, v50
	v_exp_f32_e32 v5, v51
	v_exp_f32_e32 v6, v52
	v_exp_f32_e32 v7, v53
	v_exp_f32_e32 v8, v54
	v_exp_f32_e32 v9, v55
	v_pk_add_f32 v[244:245], v[4:5], v[6:7]
	v_exp_f32_e32 v10, v56
	v_exp_f32_e32 v11, v57
	v_pk_add_f32 v[244:245], v[244:245], v[8:9]
	v_exp_f32_e32 v12, v58
	v_exp_f32_e32 v13, v59
	v_pk_add_f32 v[244:245], v[244:245], v[10:11]
	v_exp_f32_e32 v14, v60
	v_exp_f32_e32 v15, v61
	v_pk_add_f32 v[244:245], v[244:245], v[12:13]
	v_exp_f32_e32 v16, v62
	v_exp_f32_e32 v17, v63
	v_pk_add_f32 v[244:245], v[244:245], v[14:15]
	v_exp_f32_e32 v130, v64
	v_exp_f32_e32 v131, v65
	v_pk_add_f32 v[244:245], v[244:245], v[16:17]
	v_exp_f32_e32 v132, v66
	v_exp_f32_e32 v133, v67
	v_pk_add_f32 v[244:245], v[244:245], v[130:131]
	v_exp_f32_e32 v134, v68
	v_exp_f32_e32 v135, v69
	v_pk_add_f32 v[244:245], v[244:245], v[132:133]
	v_exp_f32_e32 v136, v70
	v_exp_f32_e32 v137, v71
	v_pk_add_f32 v[244:245], v[244:245], v[134:135]
	v_exp_f32_e32 v138, v72
	v_exp_f32_e32 v139, v73
	v_pk_add_f32 v[244:245], v[244:245], v[136:137]
	v_exp_f32_e32 v140, v74
	v_exp_f32_e32 v141, v75
	v_pk_add_f32 v[244:245], v[244:245], v[138:139]
	v_exp_f32_e32 v142, v76
	v_exp_f32_e32 v143, v77
	v_pk_add_f32 v[244:245], v[244:245], v[140:141]
	v_exp_f32_e32 v144, v78
	v_exp_f32_e32 v145, v79
	v_pk_add_f32 v[244:245], v[244:245], v[142:143]
	v_exp_f32_e32 v146, v80
	v_exp_f32_e32 v147, v81
	v_pk_add_f32 v[244:245], v[244:245], v[144:145]
	s_nop 0
	v_pk_add_f32 v[244:245], v[244:245], v[146:147]
	v_add_f32_e32 v244, v244, v245
	v_cvt_pk_bf16_f32 v4, v4, v5
	v_cvt_pk_bf16_f32 v5, v6, v7
	v_cvt_pk_bf16_f32 v6, v8, v9
	v_cvt_pk_bf16_f32 v7, v10, v11
	v_cvt_pk_bf16_f32 v8, v12, v13
	v_cvt_pk_bf16_f32 v9, v14, v15
	v_cvt_pk_bf16_f32 v10, v16, v17
	v_cvt_pk_bf16_f32 v11, v130, v131
	v_fmac_f32_e32 v244, v172, v2
	v_cvt_pk_bf16_f32 v12, v132, v133
	v_cvt_pk_bf16_f32 v13, v134, v135
	v_cvt_pk_bf16_f32 v14, v136, v137
	v_cvt_pk_bf16_f32 v15, v138, v139
	v_cvt_pk_bf16_f32 v68, v140, v141
	v_cvt_pk_bf16_f32 v69, v142, v143
	v_cvt_pk_bf16_f32 v70, v144, v145
	v_cvt_pk_bf16_f32 v71, v146, v147
	s_waitcnt lgkmcnt(0)
	v_mfma_f32_32x32x16_bf16 v[34:49], v[188:191], v[4:7], v[34:49]
	v_mfma_f32_32x32x16_bf16 v[18:33], v[192:195], v[4:7], v[18:33]
	v_mfma_f32_32x32x16_bf16 v[34:49], v[196:199], v[8:11], v[34:49]
	v_mfma_f32_32x32x16_bf16 v[18:33], v[200:203], v[8:11], v[18:33]
	v_mfma_f32_32x32x16_bf16 v[34:49], v[204:207], v[12:15], v[34:49]
	v_mfma_f32_32x32x16_bf16 v[18:33], v[208:211], v[12:15], v[18:33]
	v_mfma_f32_32x32x16_bf16 v[34:49], v[212:215], v[68:71], v[34:49]
	v_mfma_f32_32x32x16_bf16 v[18:33], v[216:219], v[68:71], v[18:33]
	v_mov_b32_e32 v172, v244
	s_branch .LBB0_463

.LBB0_463:
	s_add_i32 s23, s23, 1
	v_subrev_u32_e32 v119, 64, v119
	s_add_i32 s64, s64, -1
	v_add_u32_e32 v128, 64, v128
	s_and_b64 vcc, exec, s[26:27]
	s_cbranch_vccnz .LBB0_466
	s_nop 0
	s_branch .LBB0_452
